# SwiGLU epilogue: remaining dead division-helper chains removed, wait-state padding re-derived
# baseline (speedup 1.0000x reference)
.LBB0_686:
	s_or_b64 exec, exec, s[38:39]
	v_mul_f32_e32 v131, 0xbfb8aa3b, v124
	v_exp_f32_e32 v132, v131
	v_mul_f32_e32 v131, 0xbfb8aa3b, v125
	v_exp_f32_e32 v133, v131
	v_or_b32_e32 v130, s30, v146
	s_lshl_b32 s38, s56, 7
	v_lshlrev_b32_e32 v131, 4, v145
	v_pk_add_f32 v[132:133], v[132:133], 1.0 op_sel_hi:[1,0]
	v_lshlrev_b32_e32 v134, 2, v144
	v_or3_b32 v134, v131, s38, v134
	v_add_u32_e32 v130, v130, v147
	v_ashrrev_i32_e32 v135, 31, v134
	v_div_scale_f32 v139, s[30:31], v132, v132, v124
	v_rcp_f32_e32 v140, v139
	v_rcp_f32_e32 v131, v133
	s_nop 0
	v_mul_f32_e32 v125, v125, v131
	v_fma_f32 v131, -v139, v140, 1.0
	v_fmac_f32_e32 v140, v131, v140
	v_mul_f32_e32 v136, 0xbfb8aa3b, v126
	v_mul_f32_e32 v137, 0xbfb8aa3b, v127
	v_exp_f32_e32 v136, v136
	v_exp_f32_e32 v137, v137
	v_rcp_f32_e32 v131, v132
	s_nop 0
	v_mul_f32_e32 v124, v124, v131
	v_pk_add_f32 v[136:137], v[136:137], 1.0 op_sel_hi:[1,0]
	v_pk_mul_f32 v[120:121], v[120:121], v[124:125]
	v_div_scale_f32 v133, s[30:31], v137, v137, v127
	v_rcp_f32_e32 v138, v133
	v_cvt_pk_bf16_f32 v132, v120, v121
	v_fma_f32 v120, -v133, v138, 1.0
	v_fmac_f32_e32 v138, v120, v138
	v_rcp_f32_e32 v120, v137
	s_nop 0
	v_mul_f32_e32 v121, v127, v120
	v_rcp_f32_e32 v120, v136
	s_nop 0
	v_mul_f32_e32 v120, v126, v120
	v_pk_mul_f32 v[120:121], v[122:123], v[120:121]
	v_lshlrev_b64 v[122:123], 1, v[134:135]
	v_cvt_pk_bf16_f32 v133, v120, v121
	v_mov_b64_e32 v[120:121], s[6:7]
	v_mad_i64_i32 v[124:125], s[30:31], v130, s53, v[120:121]
	v_lshl_add_u64 v[124:125], v[124:125], 0, v[122:123]
	flat_store_dwordx2 v[124:125], v[132:133]
	v_mul_f32_e32 v126, 0xbfb8aa3b, v116
	v_mul_f32_e32 v127, 0xbfb8aa3b, v117
	v_exp_f32_e32 v126, v126
	v_exp_f32_e32 v127, v127
	v_or_b32_e32 v134, 16, v130
	v_pk_add_f32 v[126:127], v[126:127], 1.0 op_sel_hi:[1,0]
	s_nop 0
	v_div_scale_f32 v136, s[30:31], v126, v126, v116
	v_rcp_f32_e32 v137, v136
	v_rcp_f32_e32 v131, v127
	s_nop 0
	v_mul_f32_e32 v117, v117, v131
	v_fma_f32 v127, -v136, v137, 1.0
	v_fmac_f32_e32 v137, v127, v137
	v_mul_f32_e32 v132, 0xbfb8aa3b, v118
	v_mul_f32_e32 v133, 0xbfb8aa3b, v119
	v_exp_f32_e32 v132, v132
	v_exp_f32_e32 v133, v133
	v_rcp_f32_e32 v127, v126
	s_nop 0
	v_mul_f32_e32 v116, v116, v127
	v_pk_add_f32 v[132:133], v[132:133], 1.0 op_sel_hi:[1,0]
	v_pk_mul_f32 v[112:113], v[112:113], v[116:117]
	v_div_scale_f32 v131, s[30:31], v133, v133, v119
	v_rcp_f32_e32 v135, v131
	v_cvt_pk_bf16_f32 v116, v112, v113
	v_fma_f32 v112, -v131, v135, 1.0
	v_fmac_f32_e32 v135, v112, v135
	v_rcp_f32_e32 v112, v133
	s_nop 0
	v_mul_f32_e32 v113, v119, v112
	v_rcp_f32_e32 v112, v132
	s_nop 0
	v_mul_f32_e32 v112, v118, v112
	v_pk_mul_f32 v[112:113], v[114:115], v[112:113]
	s_nop 0
	v_cvt_pk_bf16_f32 v117, v112, v113
	v_mad_i64_i32 v[112:113], s[30:31], v134, s53, v[120:121]
	v_lshl_add_u64 v[112:113], v[112:113], 0, v[122:123]
	flat_store_dwordx2 v[112:113], v[116:117]
	v_mul_f32_e32 v114, 0xbfb8aa3b, v108
	v_mul_f32_e32 v115, 0xbfb8aa3b, v109
	v_exp_f32_e32 v114, v114
	v_exp_f32_e32 v115, v115
	v_or_b32_e32 v118, 32, v130
	v_pk_add_f32 v[114:115], v[114:115], 1.0 op_sel_hi:[1,0]
	s_nop 0
	v_rcp_f32_e32 v116, v115
	s_nop 0
	v_mul_f32_e32 v109, v109, v116
	v_mul_f32_e32 v117, 0xbfb8aa3b, v111
	v_mul_f32_e32 v116, 0xbfb8aa3b, v110
	v_exp_f32_e32 v116, v116
	v_exp_f32_e32 v117, v117
	v_rcp_f32_e32 v115, v114
	s_nop 0
	v_mul_f32_e32 v108, v108, v115
	v_pk_add_f32 v[116:117], v[116:117], 1.0 op_sel_hi:[1,0]
	v_pk_mul_f32 v[104:105], v[104:105], v[108:109]
	s_nop 0
	v_cvt_pk_bf16_f32 v108, v104, v105
	v_rcp_f32_e32 v104, v117
	s_nop 0
	v_mul_f32_e32 v105, v111, v104
	v_rcp_f32_e32 v104, v116
	s_nop 0
	v_mul_f32_e32 v104, v110, v104
	v_pk_mul_f32 v[104:105], v[106:107], v[104:105]
	s_nop 0
	v_cvt_pk_bf16_f32 v109, v104, v105
	v_mad_i64_i32 v[104:105], s[30:31], v118, s53, v[120:121]
	v_lshl_add_u64 v[104:105], v[104:105], 0, v[122:123]
	flat_store_dwordx2 v[104:105], v[108:109]
	v_mul_f32_e32 v106, 0xbfb8aa3b, v100
	v_mul_f32_e32 v107, 0xbfb8aa3b, v101
	v_exp_f32_e32 v106, v106
	v_exp_f32_e32 v107, v107
	v_or_b32_e32 v110, 48, v130
	v_pk_add_f32 v[106:107], v[106:107], 1.0 op_sel_hi:[1,0]
	s_nop 0
	v_rcp_f32_e32 v108, v107
	s_nop 0
	v_mul_f32_e32 v101, v101, v108
	v_mul_f32_e32 v109, 0xbfb8aa3b, v103
	v_mul_f32_e32 v108, 0xbfb8aa3b, v102
	v_exp_f32_e32 v108, v108
	v_exp_f32_e32 v109, v109
	v_rcp_f32_e32 v107, v106
	s_nop 0
	v_mul_f32_e32 v100, v100, v107
	v_pk_add_f32 v[108:109], v[108:109], 1.0 op_sel_hi:[1,0]
	v_pk_mul_f32 v[96:97], v[96:97], v[100:101]
	s_nop 0
	v_cvt_pk_bf16_f32 v100, v96, v97
	v_rcp_f32_e32 v96, v109
	s_nop 0
	v_mul_f32_e32 v97, v103, v96
	v_rcp_f32_e32 v96, v108
	s_nop 0
	v_mul_f32_e32 v96, v102, v96
	v_pk_mul_f32 v[96:97], v[98:99], v[96:97]
	s_nop 0
	v_cvt_pk_bf16_f32 v101, v96, v97
	v_mad_i64_i32 v[96:97], s[30:31], v110, s53, v[120:121]
	v_lshl_add_u64 v[96:97], v[96:97], 0, v[122:123]
	flat_store_dwordx2 v[96:97], v[100:101]
	v_mul_f32_e32 v98, 0xbfb8aa3b, v92
	v_mul_f32_e32 v99, 0xbfb8aa3b, v93
	v_exp_f32_e32 v98, v98
	v_exp_f32_e32 v99, v99
	s_nop 0
	v_pk_add_f32 v[98:99], v[98:99], 1.0 op_sel_hi:[1,0]
	s_nop 0
	v_rcp_f32_e32 v100, v99
	s_nop 0
	v_mul_f32_e32 v93, v93, v100
	v_mul_f32_e32 v101, 0xbfb8aa3b, v95
	v_mul_f32_e32 v100, 0xbfb8aa3b, v94
	v_exp_f32_e32 v100, v100
	v_exp_f32_e32 v101, v101
	v_rcp_f32_e32 v99, v98
	s_nop 0
	v_mul_f32_e32 v92, v92, v99
	v_pk_add_f32 v[100:101], v[100:101], 1.0 op_sel_hi:[1,0]
	v_pk_mul_f32 v[88:89], v[88:89], v[92:93]
	s_nop 0
	v_cvt_pk_bf16_f32 v88, v88, v89
	v_rcp_f32_e32 v89, v101
	s_nop 0
	v_mul_f32_e32 v93, v95, v89
	v_rcp_f32_e32 v89, v100
	s_nop 0
	v_mul_f32_e32 v92, v94, v89
	v_pk_mul_f32 v[90:91], v[90:91], v[92:93]
	s_nop 0
	v_cvt_pk_bf16_f32 v89, v90, v91
	flat_store_dwordx2 v[124:125], v[88:89] offset:128
	v_mul_f32_e32 v88, 0xbfb8aa3b, v84
	v_mul_f32_e32 v89, 0xbfb8aa3b, v85
	v_exp_f32_e32 v88, v88
	v_exp_f32_e32 v89, v89
	s_nop 0
	v_pk_add_f32 v[88:89], v[88:89], 1.0 op_sel_hi:[1,0]
	s_nop 0
	v_rcp_f32_e32 v90, v89
	s_nop 0
	v_mul_f32_e32 v85, v85, v90
	v_mul_f32_e32 v91, 0xbfb8aa3b, v87
	v_mul_f32_e32 v90, 0xbfb8aa3b, v86
	v_exp_f32_e32 v90, v90
	v_exp_f32_e32 v91, v91
	v_rcp_f32_e32 v89, v88
	s_nop 0
	v_mul_f32_e32 v84, v84, v89
	v_pk_add_f32 v[90:91], v[90:91], 1.0 op_sel_hi:[1,0]
	v_pk_mul_f32 v[80:81], v[80:81], v[84:85]
	s_nop 0
	v_cvt_pk_bf16_f32 v80, v80, v81
	v_rcp_f32_e32 v81, v91
	s_nop 0
	v_mul_f32_e32 v85, v87, v81
	v_rcp_f32_e32 v81, v90
	s_nop 0
	v_mul_f32_e32 v84, v86, v81
	v_pk_mul_f32 v[82:83], v[82:83], v[84:85]
	s_nop 0
	v_cvt_pk_bf16_f32 v81, v82, v83
	flat_store_dwordx2 v[112:113], v[80:81] offset:128
	v_mul_f32_e32 v80, 0xbfb8aa3b, v76
	v_mul_f32_e32 v81, 0xbfb8aa3b, v77
	v_exp_f32_e32 v80, v80
	v_exp_f32_e32 v81, v81
	s_nop 0
	v_pk_add_f32 v[80:81], v[80:81], 1.0 op_sel_hi:[1,0]
	s_nop 0
	v_rcp_f32_e32 v82, v81
	s_nop 0
	v_mul_f32_e32 v77, v77, v82
	v_mul_f32_e32 v83, 0xbfb8aa3b, v79
	v_mul_f32_e32 v82, 0xbfb8aa3b, v78
	v_exp_f32_e32 v82, v82
	v_exp_f32_e32 v83, v83
	v_rcp_f32_e32 v81, v80
	s_nop 0
	v_mul_f32_e32 v76, v76, v81
	v_pk_add_f32 v[82:83], v[82:83], 1.0 op_sel_hi:[1,0]
	v_pk_mul_f32 v[72:73], v[72:73], v[76:77]
	s_nop 0
	v_cvt_pk_bf16_f32 v72, v72, v73
	v_rcp_f32_e32 v73, v83
	s_nop 0
	v_mul_f32_e32 v77, v79, v73
	v_rcp_f32_e32 v73, v82
	s_nop 0
	v_mul_f32_e32 v76, v78, v73
	v_pk_mul_f32 v[74:75], v[74:75], v[76:77]
	s_nop 0
	v_cvt_pk_bf16_f32 v73, v74, v75
	flat_store_dwordx2 v[104:105], v[72:73] offset:128
	v_mul_f32_e32 v72, 0xbfb8aa3b, v68
	v_mul_f32_e32 v73, 0xbfb8aa3b, v69
	v_exp_f32_e32 v72, v72
	v_exp_f32_e32 v73, v73
	s_nop 0
	v_pk_add_f32 v[72:73], v[72:73], 1.0 op_sel_hi:[1,0]
	s_nop 0
	v_rcp_f32_e32 v74, v73
	s_nop 0
	v_mul_f32_e32 v69, v69, v74
	v_mul_f32_e32 v75, 0xbfb8aa3b, v71
	v_mul_f32_e32 v74, 0xbfb8aa3b, v70
	v_exp_f32_e32 v74, v74
	v_exp_f32_e32 v75, v75
	v_rcp_f32_e32 v73, v72
	s_nop 0
	v_mul_f32_e32 v68, v68, v73
	v_pk_add_f32 v[74:75], v[74:75], 1.0 op_sel_hi:[1,0]
	v_pk_mul_f32 v[64:65], v[64:65], v[68:69]
	s_nop 0
	v_cvt_pk_bf16_f32 v64, v64, v65
	v_rcp_f32_e32 v65, v75
	s_nop 0
	v_mul_f32_e32 v69, v71, v65
	v_rcp_f32_e32 v65, v74
	s_nop 0
	v_mul_f32_e32 v68, v70, v65
	v_pk_mul_f32 v[66:67], v[66:67], v[68:69]
	s_nop 0
	v_cvt_pk_bf16_f32 v65, v66, v67
	flat_store_dwordx2 v[96:97], v[64:65] offset:128
	v_mul_f32_e32 v64, 0xbfb8aa3b, v60
	v_mul_f32_e32 v65, 0xbfb8aa3b, v61
	v_exp_f32_e32 v64, v64
	v_exp_f32_e32 v65, v65
	v_add_u32_e32 v68, 0x80, v130
	v_pk_add_f32 v[64:65], v[64:65], 1.0 op_sel_hi:[1,0]
	s_nop 0
	v_rcp_f32_e32 v66, v65
	s_nop 0
	v_mul_f32_e32 v61, v61, v66
	v_mul_f32_e32 v67, 0xbfb8aa3b, v63
	v_mul_f32_e32 v66, 0xbfb8aa3b, v62
	v_exp_f32_e32 v66, v66
	v_exp_f32_e32 v67, v67
	v_rcp_f32_e32 v65, v64
	s_nop 0
	v_mul_f32_e32 v60, v60, v65
	v_pk_add_f32 v[66:67], v[66:67], 1.0 op_sel_hi:[1,0]
	v_pk_mul_f32 v[56:57], v[56:57], v[60:61]
	s_nop 0
	v_cvt_pk_bf16_f32 v60, v56, v57
	v_rcp_f32_e32 v56, v67
	s_nop 0
	v_mul_f32_e32 v57, v63, v56
	v_rcp_f32_e32 v56, v66
	s_nop 0
	v_mul_f32_e32 v56, v62, v56
	v_pk_mul_f32 v[56:57], v[58:59], v[56:57]
	s_nop 0
	v_cvt_pk_bf16_f32 v61, v56, v57
	v_mad_i64_i32 v[56:57], s[30:31], v68, s53, v[120:121]
	v_lshl_add_u64 v[56:57], v[56:57], 0, v[122:123]
	flat_store_dwordx2 v[56:57], v[60:61]
	v_mul_f32_e32 v58, 0xbfb8aa3b, v52
	v_mul_f32_e32 v59, 0xbfb8aa3b, v53
	v_exp_f32_e32 v58, v58
	v_exp_f32_e32 v59, v59
	v_add_u32_e32 v62, 0x90, v130
	v_pk_add_f32 v[58:59], v[58:59], 1.0 op_sel_hi:[1,0]
	s_nop 0
	v_rcp_f32_e32 v60, v59
	s_nop 0
	v_mul_f32_e32 v53, v53, v60
	v_mul_f32_e32 v61, 0xbfb8aa3b, v55
	v_mul_f32_e32 v60, 0xbfb8aa3b, v54
	v_exp_f32_e32 v60, v60
	v_exp_f32_e32 v61, v61
	v_rcp_f32_e32 v59, v58
	s_nop 0
	v_mul_f32_e32 v52, v52, v59
	v_pk_add_f32 v[60:61], v[60:61], 1.0 op_sel_hi:[1,0]
	v_pk_mul_f32 v[48:49], v[48:49], v[52:53]
	s_nop 0
	v_cvt_pk_bf16_f32 v52, v48, v49
	v_rcp_f32_e32 v48, v61
	s_nop 0
	v_mul_f32_e32 v49, v55, v48
	v_rcp_f32_e32 v48, v60
	s_nop 0
	v_mul_f32_e32 v48, v54, v48
	v_pk_mul_f32 v[48:49], v[50:51], v[48:49]
	s_nop 0
	v_cvt_pk_bf16_f32 v53, v48, v49
	v_mad_i64_i32 v[48:49], s[30:31], v62, s53, v[120:121]
	v_lshl_add_u64 v[48:49], v[48:49], 0, v[122:123]
	flat_store_dwordx2 v[48:49], v[52:53]
	v_mul_f32_e32 v50, 0xbfb8aa3b, v44
	v_mul_f32_e32 v51, 0xbfb8aa3b, v45
	v_exp_f32_e32 v50, v50
	v_exp_f32_e32 v51, v51
	v_add_u32_e32 v54, 0xa0, v130
	v_pk_add_f32 v[50:51], v[50:51], 1.0 op_sel_hi:[1,0]
	s_nop 0
	v_rcp_f32_e32 v52, v51
	s_nop 0
	v_mul_f32_e32 v45, v45, v52
	v_mul_f32_e32 v53, 0xbfb8aa3b, v47
	v_mul_f32_e32 v52, 0xbfb8aa3b, v46
	v_exp_f32_e32 v52, v52
	v_exp_f32_e32 v53, v53
	v_rcp_f32_e32 v51, v50
	s_nop 0
	v_mul_f32_e32 v44, v44, v51
	v_pk_add_f32 v[52:53], v[52:53], 1.0 op_sel_hi:[1,0]
	v_pk_mul_f32 v[40:41], v[40:41], v[44:45]
	s_nop 0
	v_cvt_pk_bf16_f32 v44, v40, v41
	v_rcp_f32_e32 v40, v53
	s_nop 0
	v_mul_f32_e32 v41, v47, v40
	v_rcp_f32_e32 v40, v52
	s_nop 0
	v_mul_f32_e32 v40, v46, v40
	v_pk_mul_f32 v[40:41], v[42:43], v[40:41]
	s_nop 0
	v_cvt_pk_bf16_f32 v45, v40, v41
	v_mad_i64_i32 v[40:41], s[30:31], v54, s53, v[120:121]
	v_lshl_add_u64 v[40:41], v[40:41], 0, v[122:123]
	flat_store_dwordx2 v[40:41], v[44:45]
	v_mul_f32_e32 v42, 0xbfb8aa3b, v36
	v_mul_f32_e32 v43, 0xbfb8aa3b, v37
	v_exp_f32_e32 v42, v42
	v_exp_f32_e32 v43, v43
	v_add_u32_e32 v46, 0xb0, v130
	v_pk_add_f32 v[42:43], v[42:43], 1.0 op_sel_hi:[1,0]
	s_nop 0
	v_rcp_f32_e32 v44, v43
	s_nop 0
	v_mul_f32_e32 v37, v37, v44
	v_mul_f32_e32 v45, 0xbfb8aa3b, v39
	v_mul_f32_e32 v44, 0xbfb8aa3b, v38
	v_exp_f32_e32 v44, v44
	v_exp_f32_e32 v45, v45
	v_rcp_f32_e32 v43, v42
	s_nop 0
	v_mul_f32_e32 v36, v36, v43
	v_pk_add_f32 v[44:45], v[44:45], 1.0 op_sel_hi:[1,0]
	v_pk_mul_f32 v[32:33], v[32:33], v[36:37]
	s_nop 0
	v_cvt_pk_bf16_f32 v36, v32, v33
	v_rcp_f32_e32 v32, v45
	s_nop 0
	v_mul_f32_e32 v33, v39, v32
	v_rcp_f32_e32 v32, v44
	s_nop 0
	v_mul_f32_e32 v32, v38, v32
	v_pk_mul_f32 v[32:33], v[34:35], v[32:33]
	s_nop 0
	v_cvt_pk_bf16_f32 v37, v32, v33
	v_mad_i64_i32 v[32:33], s[30:31], v46, s53, v[120:121]
	v_lshl_add_u64 v[32:33], v[32:33], 0, v[122:123]
	flat_store_dwordx2 v[32:33], v[36:37]
	v_mul_f32_e32 v34, 0xbfb8aa3b, v28
	v_mul_f32_e32 v35, 0xbfb8aa3b, v29
	v_exp_f32_e32 v34, v34
	v_exp_f32_e32 v35, v35
	s_nop 0
	v_pk_add_f32 v[34:35], v[34:35], 1.0 op_sel_hi:[1,0]
	s_nop 0
	v_rcp_f32_e32 v36, v35
	s_nop 0
	v_mul_f32_e32 v29, v29, v36
	v_mul_f32_e32 v37, 0xbfb8aa3b, v31
	v_mul_f32_e32 v36, 0xbfb8aa3b, v30
	v_exp_f32_e32 v36, v36
	v_exp_f32_e32 v37, v37
	v_rcp_f32_e32 v35, v34
	s_nop 0
	v_mul_f32_e32 v28, v28, v35
	v_pk_add_f32 v[36:37], v[36:37], 1.0 op_sel_hi:[1,0]
	v_pk_mul_f32 v[24:25], v[24:25], v[28:29]
	s_nop 0
	v_cvt_pk_bf16_f32 v24, v24, v25
	v_rcp_f32_e32 v25, v37
	s_nop 0
	v_mul_f32_e32 v29, v31, v25
	v_rcp_f32_e32 v25, v36
	s_nop 0
	v_mul_f32_e32 v28, v30, v25
	v_pk_mul_f32 v[26:27], v[26:27], v[28:29]
	s_nop 0
	v_cvt_pk_bf16_f32 v25, v26, v27
	flat_store_dwordx2 v[56:57], v[24:25] offset:128
	v_mul_f32_e32 v24, 0xbfb8aa3b, v20
	v_mul_f32_e32 v25, 0xbfb8aa3b, v21
	v_exp_f32_e32 v24, v24
	v_exp_f32_e32 v25, v25
	s_nop 0
	v_pk_add_f32 v[24:25], v[24:25], 1.0 op_sel_hi:[1,0]
	s_nop 0
	v_rcp_f32_e32 v26, v25
	s_nop 0
	v_mul_f32_e32 v21, v21, v26
	v_mul_f32_e32 v27, 0xbfb8aa3b, v23
	v_mul_f32_e32 v26, 0xbfb8aa3b, v22
	v_exp_f32_e32 v26, v26
	v_exp_f32_e32 v27, v27
	v_rcp_f32_e32 v25, v24
	s_nop 0
	v_mul_f32_e32 v20, v20, v25
	v_pk_add_f32 v[26:27], v[26:27], 1.0 op_sel_hi:[1,0]
	v_pk_mul_f32 v[16:17], v[16:17], v[20:21]
	s_nop 0
	v_cvt_pk_bf16_f32 v16, v16, v17
	v_rcp_f32_e32 v17, v27
	s_nop 0
	v_mul_f32_e32 v21, v23, v17
	v_rcp_f32_e32 v17, v26
	s_nop 0
	v_mul_f32_e32 v20, v22, v17
	v_pk_mul_f32 v[18:19], v[18:19], v[20:21]
	s_nop 0
	v_cvt_pk_bf16_f32 v17, v18, v19
	flat_store_dwordx2 v[48:49], v[16:17] offset:128
	v_mul_f32_e32 v16, 0xbfb8aa3b, v12
	v_mul_f32_e32 v17, 0xbfb8aa3b, v13
	v_exp_f32_e32 v16, v16
	v_exp_f32_e32 v17, v17
	s_nop 0
	v_pk_add_f32 v[16:17], v[16:17], 1.0 op_sel_hi:[1,0]
	s_nop 0
	v_rcp_f32_e32 v18, v17
	s_nop 0
	v_mul_f32_e32 v13, v13, v18
	v_mul_f32_e32 v19, 0xbfb8aa3b, v15
	v_mul_f32_e32 v18, 0xbfb8aa3b, v14
	v_exp_f32_e32 v18, v18
	v_exp_f32_e32 v19, v19
	v_rcp_f32_e32 v17, v16
	s_nop 0
	v_mul_f32_e32 v12, v12, v17
	v_pk_add_f32 v[18:19], v[18:19], 1.0 op_sel_hi:[1,0]
	v_pk_mul_f32 v[8:9], v[8:9], v[12:13]
	s_nop 0
	v_cvt_pk_bf16_f32 v8, v8, v9
	v_rcp_f32_e32 v9, v19
	s_nop 0
	v_mul_f32_e32 v13, v15, v9
	v_rcp_f32_e32 v9, v18
	s_nop 0
	v_mul_f32_e32 v12, v14, v9
	v_pk_mul_f32 v[10:11], v[10:11], v[12:13]
	s_nop 0
	v_cvt_pk_bf16_f32 v9, v10, v11
	flat_store_dwordx2 v[40:41], v[8:9] offset:128
	v_mul_f32_e32 v8, 0xbfb8aa3b, v4
	v_mul_f32_e32 v9, 0xbfb8aa3b, v5
	v_exp_f32_e32 v8, v8
	v_exp_f32_e32 v9, v9
	s_nop 0
	v_pk_add_f32 v[8:9], v[8:9], 1.0 op_sel_hi:[1,0]
	s_nop 0
	v_rcp_f32_e32 v10, v9
	s_nop 0
	v_mul_f32_e32 v5, v5, v10
	v_mul_f32_e32 v11, 0xbfb8aa3b, v7
	v_mul_f32_e32 v10, 0xbfb8aa3b, v6
	v_exp_f32_e32 v10, v10
	v_exp_f32_e32 v11, v11
	v_rcp_f32_e32 v9, v8
	s_nop 0
	v_mul_f32_e32 v4, v4, v9
	v_pk_add_f32 v[10:11], v[10:11], 1.0 op_sel_hi:[1,0]
	v_pk_mul_f32 v[0:1], v[0:1], v[4:5]
	s_nop 0
	v_cvt_pk_bf16_f32 v0, v0, v1
	v_div_scale_f32 v8, s[30:31], v10, v10, v6
	v_rcp_f32_e32 v1, v11
	s_nop 0
	v_mul_f32_e32 v5, v7, v1
	v_rcp_f32_e32 v1, v10
	s_nop 0
	v_mul_f32_e32 v4, v6, v1
	v_pk_mul_f32 v[2:3], v[2:3], v[4:5]
	s_nop 0
	v_cvt_pk_bf16_f32 v1, v2, v3
	flat_store_dwordx2 v[32:33], v[0:1] offset:128
	s_andn2_b64 vcc, exec, s[0:1]
	s_mov_b32 s56, s54
	s_mov_b32 s38, s55
	s_cbranch_vccz .LBB0_695

.LBB0_1800:
	s_or_b64 exec, exec, s[38:39]
	v_mul_f32_e32 v131, 0xbfb8aa3b, v124
	v_exp_f32_e32 v132, v131
	v_mul_f32_e32 v131, 0xbfb8aa3b, v125
	v_exp_f32_e32 v133, v131
	v_or_b32_e32 v130, s30, v152
	s_lshl_b32 s38, s56, 7
	v_lshlrev_b32_e32 v131, 4, v145
	v_pk_add_f32 v[132:133], v[132:133], 1.0 op_sel_hi:[1,0]
	v_lshlrev_b32_e32 v134, 2, v144
	v_or3_b32 v134, v131, s38, v134
	v_add_u32_e32 v130, v130, v153
	v_ashrrev_i32_e32 v135, 31, v134
	v_div_scale_f32 v139, s[30:31], v132, v132, v124
	v_rcp_f32_e32 v140, v139
	v_rcp_f32_e32 v131, v133
	s_nop 0
	v_mul_f32_e32 v125, v125, v131
	v_fma_f32 v131, -v139, v140, 1.0
	v_fmac_f32_e32 v140, v131, v140
	v_mul_f32_e32 v136, 0xbfb8aa3b, v126
	v_mul_f32_e32 v137, 0xbfb8aa3b, v127
	v_exp_f32_e32 v136, v136
	v_exp_f32_e32 v137, v137
	v_rcp_f32_e32 v131, v132
	s_nop 0
	v_mul_f32_e32 v124, v124, v131
	v_pk_add_f32 v[136:137], v[136:137], 1.0 op_sel_hi:[1,0]
	v_pk_mul_f32 v[120:121], v[120:121], v[124:125]
	v_div_scale_f32 v133, s[30:31], v137, v137, v127
	v_rcp_f32_e32 v138, v133
	v_cvt_pk_bf16_f32 v132, v120, v121
	v_fma_f32 v120, -v133, v138, 1.0
	v_fmac_f32_e32 v138, v120, v138
	v_rcp_f32_e32 v120, v137
	s_nop 0
	v_mul_f32_e32 v121, v127, v120
	v_rcp_f32_e32 v120, v136
	s_nop 0
	v_mul_f32_e32 v120, v126, v120
	v_pk_mul_f32 v[120:121], v[122:123], v[120:121]
	v_lshlrev_b64 v[122:123], 1, v[134:135]
	v_cvt_pk_bf16_f32 v133, v120, v121
	v_mov_b64_e32 v[120:121], s[6:7]
	v_mad_i64_i32 v[124:125], s[30:31], v130, s53, v[120:121]
	v_lshl_add_u64 v[124:125], v[124:125], 0, v[122:123]
	flat_store_dwordx2 v[124:125], v[132:133]
	v_mul_f32_e32 v126, 0xbfb8aa3b, v116
	v_mul_f32_e32 v127, 0xbfb8aa3b, v117
	v_exp_f32_e32 v126, v126
	v_exp_f32_e32 v127, v127
	v_or_b32_e32 v134, 16, v130
	v_pk_add_f32 v[126:127], v[126:127], 1.0 op_sel_hi:[1,0]
	s_nop 0
	v_div_scale_f32 v136, s[30:31], v126, v126, v116
	v_rcp_f32_e32 v137, v136
	v_rcp_f32_e32 v131, v127
	s_nop 0
	v_mul_f32_e32 v117, v117, v131
	v_fma_f32 v127, -v136, v137, 1.0
	v_fmac_f32_e32 v137, v127, v137
	v_mul_f32_e32 v132, 0xbfb8aa3b, v118
	v_mul_f32_e32 v133, 0xbfb8aa3b, v119
	v_exp_f32_e32 v132, v132
	v_exp_f32_e32 v133, v133
	v_rcp_f32_e32 v127, v126
	s_nop 0
	v_mul_f32_e32 v116, v116, v127
	v_pk_add_f32 v[132:133], v[132:133], 1.0 op_sel_hi:[1,0]
	v_pk_mul_f32 v[112:113], v[112:113], v[116:117]
	v_div_scale_f32 v131, s[30:31], v133, v133, v119
	v_rcp_f32_e32 v135, v131
	v_cvt_pk_bf16_f32 v116, v112, v113
	v_fma_f32 v112, -v131, v135, 1.0
	v_fmac_f32_e32 v135, v112, v135
	v_rcp_f32_e32 v112, v133
	s_nop 0
	v_mul_f32_e32 v113, v119, v112
	v_rcp_f32_e32 v112, v132
	s_nop 0
	v_mul_f32_e32 v112, v118, v112
	v_pk_mul_f32 v[112:113], v[114:115], v[112:113]
	s_nop 0
	v_cvt_pk_bf16_f32 v117, v112, v113
	v_mad_i64_i32 v[112:113], s[30:31], v134, s53, v[120:121]
	v_lshl_add_u64 v[112:113], v[112:113], 0, v[122:123]
	flat_store_dwordx2 v[112:113], v[116:117]
	v_mul_f32_e32 v114, 0xbfb8aa3b, v108
	v_mul_f32_e32 v115, 0xbfb8aa3b, v109
	v_exp_f32_e32 v114, v114
	v_exp_f32_e32 v115, v115
	v_or_b32_e32 v118, 32, v130
	v_pk_add_f32 v[114:115], v[114:115], 1.0 op_sel_hi:[1,0]
	s_nop 0
	v_rcp_f32_e32 v116, v115
	s_nop 0
	v_mul_f32_e32 v109, v109, v116
	v_mul_f32_e32 v117, 0xbfb8aa3b, v111
	v_mul_f32_e32 v116, 0xbfb8aa3b, v110
	v_exp_f32_e32 v116, v116
	v_exp_f32_e32 v117, v117
	v_rcp_f32_e32 v115, v114
	s_nop 0
	v_mul_f32_e32 v108, v108, v115
	v_pk_add_f32 v[116:117], v[116:117], 1.0 op_sel_hi:[1,0]
	v_pk_mul_f32 v[104:105], v[104:105], v[108:109]
	s_nop 0
	v_cvt_pk_bf16_f32 v108, v104, v105
	v_rcp_f32_e32 v104, v117
	s_nop 0
	v_mul_f32_e32 v105, v111, v104
	v_rcp_f32_e32 v104, v116
	s_nop 0
	v_mul_f32_e32 v104, v110, v104
	v_pk_mul_f32 v[104:105], v[106:107], v[104:105]
	s_nop 0
	v_cvt_pk_bf16_f32 v109, v104, v105
	v_mad_i64_i32 v[104:105], s[30:31], v118, s53, v[120:121]
	v_lshl_add_u64 v[104:105], v[104:105], 0, v[122:123]
	flat_store_dwordx2 v[104:105], v[108:109]
	v_mul_f32_e32 v106, 0xbfb8aa3b, v100
	v_mul_f32_e32 v107, 0xbfb8aa3b, v101
	v_exp_f32_e32 v106, v106
	v_exp_f32_e32 v107, v107
	v_or_b32_e32 v110, 48, v130
	v_pk_add_f32 v[106:107], v[106:107], 1.0 op_sel_hi:[1,0]
	s_nop 0
	v_rcp_f32_e32 v108, v107
	s_nop 0
	v_mul_f32_e32 v101, v101, v108
	v_mul_f32_e32 v109, 0xbfb8aa3b, v103
	v_mul_f32_e32 v108, 0xbfb8aa3b, v102
	v_exp_f32_e32 v108, v108
	v_exp_f32_e32 v109, v109
	v_rcp_f32_e32 v107, v106
	s_nop 0
	v_mul_f32_e32 v100, v100, v107
	v_pk_add_f32 v[108:109], v[108:109], 1.0 op_sel_hi:[1,0]
	v_pk_mul_f32 v[96:97], v[96:97], v[100:101]
	s_nop 0
	v_cvt_pk_bf16_f32 v100, v96, v97
	v_rcp_f32_e32 v96, v109
	s_nop 0
	v_mul_f32_e32 v97, v103, v96
	v_rcp_f32_e32 v96, v108
	s_nop 0
	v_mul_f32_e32 v96, v102, v96
	v_pk_mul_f32 v[96:97], v[98:99], v[96:97]
	s_nop 0
	v_cvt_pk_bf16_f32 v101, v96, v97
	v_mad_i64_i32 v[96:97], s[30:31], v110, s53, v[120:121]
	v_lshl_add_u64 v[96:97], v[96:97], 0, v[122:123]
	flat_store_dwordx2 v[96:97], v[100:101]
	v_mul_f32_e32 v98, 0xbfb8aa3b, v92
	v_mul_f32_e32 v99, 0xbfb8aa3b, v93
	v_exp_f32_e32 v98, v98
	v_exp_f32_e32 v99, v99
	s_nop 0
	v_pk_add_f32 v[98:99], v[98:99], 1.0 op_sel_hi:[1,0]
	s_nop 0
	v_rcp_f32_e32 v100, v99
	s_nop 0
	v_mul_f32_e32 v93, v93, v100
	v_mul_f32_e32 v101, 0xbfb8aa3b, v95
	v_mul_f32_e32 v100, 0xbfb8aa3b, v94
	v_exp_f32_e32 v100, v100
	v_exp_f32_e32 v101, v101
	v_rcp_f32_e32 v99, v98
	s_nop 0
	v_mul_f32_e32 v92, v92, v99
	v_pk_add_f32 v[100:101], v[100:101], 1.0 op_sel_hi:[1,0]
	v_pk_mul_f32 v[88:89], v[88:89], v[92:93]
	s_nop 0
	v_cvt_pk_bf16_f32 v88, v88, v89
	v_rcp_f32_e32 v89, v101
	s_nop 0
	v_mul_f32_e32 v93, v95, v89
	v_rcp_f32_e32 v89, v100
	s_nop 0
	v_mul_f32_e32 v92, v94, v89
	v_pk_mul_f32 v[90:91], v[90:91], v[92:93]
	s_nop 0
	v_cvt_pk_bf16_f32 v89, v90, v91
	flat_store_dwordx2 v[124:125], v[88:89] offset:128
	v_mul_f32_e32 v88, 0xbfb8aa3b, v84
	v_mul_f32_e32 v89, 0xbfb8aa3b, v85
	v_exp_f32_e32 v88, v88
	v_exp_f32_e32 v89, v89
	s_nop 0
	v_pk_add_f32 v[88:89], v[88:89], 1.0 op_sel_hi:[1,0]
	s_nop 0
	v_rcp_f32_e32 v90, v89
	s_nop 0
	v_mul_f32_e32 v85, v85, v90
	v_mul_f32_e32 v91, 0xbfb8aa3b, v87
	v_mul_f32_e32 v90, 0xbfb8aa3b, v86
	v_exp_f32_e32 v90, v90
	v_exp_f32_e32 v91, v91
	v_rcp_f32_e32 v89, v88
	s_nop 0
	v_mul_f32_e32 v84, v84, v89
	v_pk_add_f32 v[90:91], v[90:91], 1.0 op_sel_hi:[1,0]
	v_pk_mul_f32 v[80:81], v[80:81], v[84:85]
	s_nop 0
	v_cvt_pk_bf16_f32 v80, v80, v81
	v_rcp_f32_e32 v81, v91
	s_nop 0
	v_mul_f32_e32 v85, v87, v81
	v_rcp_f32_e32 v81, v90
	s_nop 0
	v_mul_f32_e32 v84, v86, v81
	v_pk_mul_f32 v[82:83], v[82:83], v[84:85]
	s_nop 0
	v_cvt_pk_bf16_f32 v81, v82, v83
	flat_store_dwordx2 v[112:113], v[80:81] offset:128
	v_mul_f32_e32 v80, 0xbfb8aa3b, v76
	v_mul_f32_e32 v81, 0xbfb8aa3b, v77
	v_exp_f32_e32 v80, v80
	v_exp_f32_e32 v81, v81
	s_nop 0
	v_pk_add_f32 v[80:81], v[80:81], 1.0 op_sel_hi:[1,0]
	s_nop 0
	v_rcp_f32_e32 v82, v81
	s_nop 0
	v_mul_f32_e32 v77, v77, v82
	v_mul_f32_e32 v83, 0xbfb8aa3b, v79
	v_mul_f32_e32 v82, 0xbfb8aa3b, v78
	v_exp_f32_e32 v82, v82
	v_exp_f32_e32 v83, v83
	v_rcp_f32_e32 v81, v80
	s_nop 0
	v_mul_f32_e32 v76, v76, v81
	v_pk_add_f32 v[82:83], v[82:83], 1.0 op_sel_hi:[1,0]
	v_pk_mul_f32 v[72:73], v[72:73], v[76:77]
	s_nop 0
	v_cvt_pk_bf16_f32 v72, v72, v73
	v_rcp_f32_e32 v73, v83
	s_nop 0
	v_mul_f32_e32 v77, v79, v73
	v_rcp_f32_e32 v73, v82
	s_nop 0
	v_mul_f32_e32 v76, v78, v73
	v_pk_mul_f32 v[74:75], v[74:75], v[76:77]
	s_nop 0
	v_cvt_pk_bf16_f32 v73, v74, v75
	flat_store_dwordx2 v[104:105], v[72:73] offset:128
	v_mul_f32_e32 v72, 0xbfb8aa3b, v68
	v_mul_f32_e32 v73, 0xbfb8aa3b, v69
	v_exp_f32_e32 v72, v72
	v_exp_f32_e32 v73, v73
	s_nop 0
	v_pk_add_f32 v[72:73], v[72:73], 1.0 op_sel_hi:[1,0]
	s_nop 0
	v_rcp_f32_e32 v74, v73
	s_nop 0
	v_mul_f32_e32 v69, v69, v74
	v_mul_f32_e32 v75, 0xbfb8aa3b, v71
	v_mul_f32_e32 v74, 0xbfb8aa3b, v70
	v_exp_f32_e32 v74, v74
	v_exp_f32_e32 v75, v75
	v_rcp_f32_e32 v73, v72
	s_nop 0
	v_mul_f32_e32 v68, v68, v73
	v_pk_add_f32 v[74:75], v[74:75], 1.0 op_sel_hi:[1,0]
	v_pk_mul_f32 v[64:65], v[64:65], v[68:69]
	s_nop 0
	v_cvt_pk_bf16_f32 v64, v64, v65
	v_rcp_f32_e32 v65, v75
	s_nop 0
	v_mul_f32_e32 v69, v71, v65
	v_rcp_f32_e32 v65, v74
	s_nop 0
	v_mul_f32_e32 v68, v70, v65
	v_pk_mul_f32 v[66:67], v[66:67], v[68:69]
	s_nop 0
	v_cvt_pk_bf16_f32 v65, v66, v67
	flat_store_dwordx2 v[96:97], v[64:65] offset:128
	v_mul_f32_e32 v64, 0xbfb8aa3b, v60
	v_mul_f32_e32 v65, 0xbfb8aa3b, v61
	v_exp_f32_e32 v64, v64
	v_exp_f32_e32 v65, v65
	v_add_u32_e32 v68, 0x80, v130
	v_pk_add_f32 v[64:65], v[64:65], 1.0 op_sel_hi:[1,0]
	s_nop 0
	v_rcp_f32_e32 v66, v65
	s_nop 0
	v_mul_f32_e32 v61, v61, v66
	v_mul_f32_e32 v67, 0xbfb8aa3b, v63
	v_mul_f32_e32 v66, 0xbfb8aa3b, v62
	v_exp_f32_e32 v66, v66
	v_exp_f32_e32 v67, v67
	v_rcp_f32_e32 v65, v64
	s_nop 0
	v_mul_f32_e32 v60, v60, v65
	v_pk_add_f32 v[66:67], v[66:67], 1.0 op_sel_hi:[1,0]
	v_pk_mul_f32 v[56:57], v[56:57], v[60:61]
	s_nop 0
	v_cvt_pk_bf16_f32 v60, v56, v57
	v_rcp_f32_e32 v56, v67
	s_nop 0
	v_mul_f32_e32 v57, v63, v56
	v_rcp_f32_e32 v56, v66
	s_nop 0
	v_mul_f32_e32 v56, v62, v56
	v_pk_mul_f32 v[56:57], v[58:59], v[56:57]
	s_nop 0
	v_cvt_pk_bf16_f32 v61, v56, v57
	v_mad_i64_i32 v[56:57], s[30:31], v68, s53, v[120:121]
	v_lshl_add_u64 v[56:57], v[56:57], 0, v[122:123]
	flat_store_dwordx2 v[56:57], v[60:61]
	v_mul_f32_e32 v58, 0xbfb8aa3b, v52
	v_mul_f32_e32 v59, 0xbfb8aa3b, v53
	v_exp_f32_e32 v58, v58
	v_exp_f32_e32 v59, v59
	v_add_u32_e32 v62, 0x90, v130
	v_pk_add_f32 v[58:59], v[58:59], 1.0 op_sel_hi:[1,0]
	s_nop 0
	v_rcp_f32_e32 v60, v59
	s_nop 0
	v_mul_f32_e32 v53, v53, v60
	v_mul_f32_e32 v61, 0xbfb8aa3b, v55
	v_mul_f32_e32 v60, 0xbfb8aa3b, v54
	v_exp_f32_e32 v60, v60
	v_exp_f32_e32 v61, v61
	v_rcp_f32_e32 v59, v58
	s_nop 0
	v_mul_f32_e32 v52, v52, v59
	v_pk_add_f32 v[60:61], v[60:61], 1.0 op_sel_hi:[1,0]
	v_pk_mul_f32 v[48:49], v[48:49], v[52:53]
	s_nop 0
	v_cvt_pk_bf16_f32 v52, v48, v49
	v_rcp_f32_e32 v48, v61
	s_nop 0
	v_mul_f32_e32 v49, v55, v48
	v_rcp_f32_e32 v48, v60
	s_nop 0
	v_mul_f32_e32 v48, v54, v48
	v_pk_mul_f32 v[48:49], v[50:51], v[48:49]
	s_nop 0
	v_cvt_pk_bf16_f32 v53, v48, v49
	v_mad_i64_i32 v[48:49], s[30:31], v62, s53, v[120:121]
	v_lshl_add_u64 v[48:49], v[48:49], 0, v[122:123]
	flat_store_dwordx2 v[48:49], v[52:53]
	v_mul_f32_e32 v50, 0xbfb8aa3b, v44
	v_mul_f32_e32 v51, 0xbfb8aa3b, v45
	v_exp_f32_e32 v50, v50
	v_exp_f32_e32 v51, v51
	v_add_u32_e32 v54, 0xa0, v130
	v_pk_add_f32 v[50:51], v[50:51], 1.0 op_sel_hi:[1,0]
	s_nop 0
	v_rcp_f32_e32 v52, v51
	s_nop 0
	v_mul_f32_e32 v45, v45, v52
	v_mul_f32_e32 v53, 0xbfb8aa3b, v47
	v_mul_f32_e32 v52, 0xbfb8aa3b, v46
	v_exp_f32_e32 v52, v52
	v_exp_f32_e32 v53, v53
	v_rcp_f32_e32 v51, v50
	s_nop 0
	v_mul_f32_e32 v44, v44, v51
	v_pk_add_f32 v[52:53], v[52:53], 1.0 op_sel_hi:[1,0]
	v_pk_mul_f32 v[40:41], v[40:41], v[44:45]
	s_nop 0
	v_cvt_pk_bf16_f32 v44, v40, v41
	v_rcp_f32_e32 v40, v53
	s_nop 0
	v_mul_f32_e32 v41, v47, v40
	v_rcp_f32_e32 v40, v52
	s_nop 0
	v_mul_f32_e32 v40, v46, v40
	v_pk_mul_f32 v[40:41], v[42:43], v[40:41]
	s_nop 0
	v_cvt_pk_bf16_f32 v45, v40, v41
	v_mad_i64_i32 v[40:41], s[30:31], v54, s53, v[120:121]
	v_lshl_add_u64 v[40:41], v[40:41], 0, v[122:123]
	flat_store_dwordx2 v[40:41], v[44:45]
	v_mul_f32_e32 v42, 0xbfb8aa3b, v36
	v_mul_f32_e32 v43, 0xbfb8aa3b, v37
	v_exp_f32_e32 v42, v42
	v_exp_f32_e32 v43, v43
	v_add_u32_e32 v46, 0xb0, v130
	v_pk_add_f32 v[42:43], v[42:43], 1.0 op_sel_hi:[1,0]
	s_nop 0
	v_rcp_f32_e32 v44, v43
	s_nop 0
	v_mul_f32_e32 v37, v37, v44
	v_mul_f32_e32 v45, 0xbfb8aa3b, v39
	v_mul_f32_e32 v44, 0xbfb8aa3b, v38
	v_exp_f32_e32 v44, v44
	v_exp_f32_e32 v45, v45
	v_rcp_f32_e32 v43, v42
	s_nop 0
	v_mul_f32_e32 v36, v36, v43
	v_pk_add_f32 v[44:45], v[44:45], 1.0 op_sel_hi:[1,0]
	v_pk_mul_f32 v[32:33], v[32:33], v[36:37]
	s_nop 0
	v_cvt_pk_bf16_f32 v36, v32, v33
	v_rcp_f32_e32 v32, v45
	s_nop 0
	v_mul_f32_e32 v33, v39, v32
	v_rcp_f32_e32 v32, v44
	s_nop 0
	v_mul_f32_e32 v32, v38, v32
	v_pk_mul_f32 v[32:33], v[34:35], v[32:33]
	s_nop 0
	v_cvt_pk_bf16_f32 v37, v32, v33
	v_mad_i64_i32 v[32:33], s[30:31], v46, s53, v[120:121]
	v_lshl_add_u64 v[32:33], v[32:33], 0, v[122:123]
	flat_store_dwordx2 v[32:33], v[36:37]
	v_mul_f32_e32 v34, 0xbfb8aa3b, v28
	v_mul_f32_e32 v35, 0xbfb8aa3b, v29
	v_exp_f32_e32 v34, v34
	v_exp_f32_e32 v35, v35
	s_nop 0
	v_pk_add_f32 v[34:35], v[34:35], 1.0 op_sel_hi:[1,0]
	s_nop 0
	v_rcp_f32_e32 v36, v35
	s_nop 0
	v_mul_f32_e32 v29, v29, v36
	v_mul_f32_e32 v37, 0xbfb8aa3b, v31
	v_mul_f32_e32 v36, 0xbfb8aa3b, v30
	v_exp_f32_e32 v36, v36
	v_exp_f32_e32 v37, v37
	v_rcp_f32_e32 v35, v34
	s_nop 0
	v_mul_f32_e32 v28, v28, v35
	v_pk_add_f32 v[36:37], v[36:37], 1.0 op_sel_hi:[1,0]
	v_pk_mul_f32 v[24:25], v[24:25], v[28:29]
	s_nop 0
	v_cvt_pk_bf16_f32 v24, v24, v25
	v_rcp_f32_e32 v25, v37
	s_nop 0
	v_mul_f32_e32 v29, v31, v25
	v_rcp_f32_e32 v25, v36
	s_nop 0
	v_mul_f32_e32 v28, v30, v25
	v_pk_mul_f32 v[26:27], v[26:27], v[28:29]
	s_nop 0
	v_cvt_pk_bf16_f32 v25, v26, v27
	flat_store_dwordx2 v[56:57], v[24:25] offset:128
	v_mul_f32_e32 v24, 0xbfb8aa3b, v20
	v_mul_f32_e32 v25, 0xbfb8aa3b, v21
	v_exp_f32_e32 v24, v24
	v_exp_f32_e32 v25, v25
	s_nop 0
	v_pk_add_f32 v[24:25], v[24:25], 1.0 op_sel_hi:[1,0]
	s_nop 0
	v_rcp_f32_e32 v26, v25
	s_nop 0
	v_mul_f32_e32 v21, v21, v26
	v_mul_f32_e32 v27, 0xbfb8aa3b, v23
	v_mul_f32_e32 v26, 0xbfb8aa3b, v22
	v_exp_f32_e32 v26, v26
	v_exp_f32_e32 v27, v27
	v_rcp_f32_e32 v25, v24
	s_nop 0
	v_mul_f32_e32 v20, v20, v25
	v_pk_add_f32 v[26:27], v[26:27], 1.0 op_sel_hi:[1,0]
	v_pk_mul_f32 v[16:17], v[16:17], v[20:21]
	s_nop 0
	v_cvt_pk_bf16_f32 v16, v16, v17
	v_rcp_f32_e32 v17, v27
	s_nop 0
	v_mul_f32_e32 v21, v23, v17
	v_rcp_f32_e32 v17, v26
	s_nop 0
	v_mul_f32_e32 v20, v22, v17
	v_pk_mul_f32 v[18:19], v[18:19], v[20:21]
	s_nop 0
	v_cvt_pk_bf16_f32 v17, v18, v19
	flat_store_dwordx2 v[48:49], v[16:17] offset:128
	v_mul_f32_e32 v16, 0xbfb8aa3b, v12
	v_mul_f32_e32 v17, 0xbfb8aa3b, v13
	v_exp_f32_e32 v16, v16
	v_exp_f32_e32 v17, v17
	s_nop 0
	v_pk_add_f32 v[16:17], v[16:17], 1.0 op_sel_hi:[1,0]
	s_nop 0
	v_rcp_f32_e32 v18, v17
	s_nop 0
	v_mul_f32_e32 v13, v13, v18
	v_mul_f32_e32 v19, 0xbfb8aa3b, v15
	v_mul_f32_e32 v18, 0xbfb8aa3b, v14
	v_exp_f32_e32 v18, v18
	v_exp_f32_e32 v19, v19
	v_rcp_f32_e32 v17, v16
	s_nop 0
	v_mul_f32_e32 v12, v12, v17
	v_pk_add_f32 v[18:19], v[18:19], 1.0 op_sel_hi:[1,0]
	v_pk_mul_f32 v[8:9], v[8:9], v[12:13]
	s_nop 0
	v_cvt_pk_bf16_f32 v8, v8, v9
	v_rcp_f32_e32 v9, v19
	s_nop 0
	v_mul_f32_e32 v13, v15, v9
	v_rcp_f32_e32 v9, v18
	s_nop 0
	v_mul_f32_e32 v12, v14, v9
	v_pk_mul_f32 v[10:11], v[10:11], v[12:13]
	s_nop 0
	v_cvt_pk_bf16_f32 v9, v10, v11
	flat_store_dwordx2 v[40:41], v[8:9] offset:128
	v_mul_f32_e32 v8, 0xbfb8aa3b, v4
	v_mul_f32_e32 v9, 0xbfb8aa3b, v5
	v_exp_f32_e32 v8, v8
	v_exp_f32_e32 v9, v9
	s_nop 0
	v_pk_add_f32 v[8:9], v[8:9], 1.0 op_sel_hi:[1,0]
	s_nop 0
	v_rcp_f32_e32 v10, v9
	s_nop 0
	v_mul_f32_e32 v5, v5, v10
	v_mul_f32_e32 v11, 0xbfb8aa3b, v7
	v_mul_f32_e32 v10, 0xbfb8aa3b, v6
	v_exp_f32_e32 v10, v10
	v_exp_f32_e32 v11, v11
	v_rcp_f32_e32 v9, v8
	s_nop 0
	v_mul_f32_e32 v4, v4, v9
	v_pk_add_f32 v[10:11], v[10:11], 1.0 op_sel_hi:[1,0]
	v_pk_mul_f32 v[0:1], v[0:1], v[4:5]
	s_nop 0
	v_cvt_pk_bf16_f32 v0, v0, v1
	v_div_scale_f32 v8, s[30:31], v10, v10, v6
	v_rcp_f32_e32 v1, v11
	s_nop 0
	v_mul_f32_e32 v5, v7, v1
	v_rcp_f32_e32 v1, v10
	s_nop 0
	v_mul_f32_e32 v4, v6, v1
	v_pk_mul_f32 v[2:3], v[2:3], v[4:5]
	s_nop 0
	v_cvt_pk_bf16_f32 v1, v2, v3
	flat_store_dwordx2 v[32:33], v[0:1] offset:128
	s_andn2_b64 vcc, exec, s[0:1]
	s_mov_b32 s56, s54
	s_mov_b32 s38, s55
	s_cbranch_vccz .LBB0_1809
